# combo11 + P3: first indexer unit's query/weight loads issued ahead of the KN block (two memory round trips overlap)
# baseline (speedup 1.0000x reference)
.LBB0_1131:
	s_cmp_lt_i32 s72, 4
	s_cselect_b64 s[4:5], -1, 0
	s_add_u32 s52, s70, 0x1d600000
	s_addc_u32 s53, s71, 0
	s_and_b64 s[82:83], s[4:5], s[0:1]
	s_andn2_b64 vcc, exec, s[82:83]
	s_cbranch_vccnz .LBB0_1547
	v_readlane_b32 s20, v255, 5
	s_add_u32 s18, s70, 0x18b00000
	s_addc_u32 s19, s71, 0
	s_lshl_b32 s21, s20, 1
	s_lshr_b32 s22, s2, 6
	s_and_b32 s22, s22, 2
	s_and_b32 s23, s2, 0x7f
	s_lshl_b32 s23, s23, 4
	s_add_i32 s23, s23, s21
	s_lshl_b32 s24, s22, 11
	s_add_i32 s24, s24, s23
	s_mov_b32 s25, 0
	s_lshl_b64 s[26:27], s[24:25], 13
	s_add_u32 s26, s18, s26
	s_addc_u32 s27, s19, s27
	s_mov_b64 s[28:29], 0x2000
	v_and_b32_e32 v209, 31, v252
	v_lshrrev_b32_e32 v223, 5, v222
	v_lshlrev_b32_e32 v0, 7, v209
	v_mov_b32_e32 v1, 0
	v_lshlrev_b32_e32 v2, 3, v223
	v_mov_b32_e32 v3, 0
	v_lshl_add_u64 v[0:1], v[0:1], 1, s[26:27]
	v_lshl_add_u64 v[0:1], v[2:3], 1, v[0:1]
	v_lshl_add_u64 v[2:3], v[0:1], 0, s[28:29]
	global_load_dwordx4 v[128:131], v[0:1], off
	global_load_dwordx4 v[132:135], v[0:1], off offset:32
	global_load_dwordx4 v[136:139], v[2:3], off
	global_load_dwordx4 v[140:143], v[2:3], off offset:32
	global_load_dwordx4 v[144:147], v[0:1], off offset:64
	global_load_dwordx4 v[148:151], v[0:1], off offset:96
	global_load_dwordx4 v[152:155], v[2:3], off offset:64
	global_load_dwordx4 v[156:159], v[2:3], off offset:96
	global_load_dwordx4 v[160:163], v[0:1], off offset:128
	global_load_dwordx4 v[164:167], v[0:1], off offset:160
	global_load_dwordx4 v[168:171], v[2:3], off offset:128
	global_load_dwordx4 v[172:175], v[2:3], off offset:160
	global_load_dwordx4 v[176:179], v[0:1], off offset:192
	global_load_dwordx4 v[180:183], v[0:1], off offset:224
	global_load_dwordx4 v[184:187], v[2:3], off offset:192
	global_load_dwordx4 v[188:191], v[2:3], off offset:224
	s_lshl_b64 s[26:27], s[24:25], 7
	s_add_u32 s26, s80, s26
	s_addc_u32 s27, s81, s27
	v_lshlrev_b32_e32 v0, 2, v223
	v_mov_b32_e32 v1, 0
	v_lshl_add_u64 v[0:1], v[0:1], 2, s[26:27]
	global_load_dwordx4 v[124:127], v[0:1], off
	global_load_dwordx4 v[116:119], v[0:1], off offset:32
	global_load_dwordx4 v[120:123], v[0:1], off offset:128
	global_load_dwordx4 v[112:115], v[0:1], off offset:160
	global_load_dwordx4 v[108:111], v[0:1], off offset:64
	global_load_dwordx4 v[100:103], v[0:1], off offset:96
	global_load_dwordx4 v[104:107], v[0:1], off offset:192
	global_load_dwordx4 v[96:99], v[0:1], off offset:224
	s_mov_b32 s32, 1
	v_mov_b32_e32 v0, v222
	s_mov_b64 s[4:5], 0x15b00000
	v_lshlrev_b32_e32 v16, 3, v0
	v_ashrrev_i32_e32 v17, 31, v16
	v_lshl_add_u64 v[18:19], v[16:17], 1, s[70:71]
	s_cmpk_lt_i32 s88, 0x2000
	s_cselect_b64 s[0:1], -1, 0
	s_cmpk_gt_i32 s88, 0x1fff
	v_lshl_add_u64 v[0:1], v[18:19], 0, s[4:5]
	s_cbranch_scc1 .LBB0_1134
	s_ashr_i32 s89, s88, 31
	s_lshl_b64 s[4:5], s[88:89], 10
	v_lshl_add_u64 v[2:3], v[0:1], 0, s[4:5]
	global_load_dwordx4 v[12:15], v[2:3], off nt
	s_branch .LBB0_1135

.LBB0_1158:
	s_lshr_b32 s0, s67, 6
	s_and_b32 s0, s0, 2
	s_ashr_i32 s1, s67, 8
	s_add_i32 s0, s0, s1
	s_and_b32 s1, s67, 0x7f
	s_xor_b32 s4, s1, 0x7f
	s_cmpk_lt_u32 s67, 0x100
	s_cselect_b32 s6, s1, s4
	s_lshl_b32 s77, s6, 4
	s_ashr_i32 s1, s0, 31
	s_add_i32 s77, s77, s35
	s_lshl_b64 s[4:5], s[0:1], 11
	s_add_u32 s88, s4, s77
	s_addc_u32 s89, s5, 0
	v_mov_b32_e32 v0, v209
	v_mov_b32_e32 v4, v223
	s_lshl_b64 s[0:1], s[0:1], 19
	s_lshl_b64 s[4:5], s[88:89], 13
	s_add_u32 s4, s18, s4
	v_lshlrev_b32_e32 v0, 7, v0
	s_addc_u32 s5, s19, s5
	v_ashrrev_i32_e32 v1, 31, v0
	v_lshlrev_b32_e32 v2, 3, v4
	v_lshl_add_u64 v[0:1], v[0:1], 1, s[4:5]
	v_ashrrev_i32_e32 v3, 31, v2
	v_lshl_add_u64 v[0:1], v[2:3], 1, v[0:1]
	s_movk_i32 s4, 0x2000
	v_add_co_u32_e32 v2, vcc, s4, v0
	s_lshl_b64 s[4:5], s[88:89], 7
	s_nop 0
	v_addc_co_u32_e32 v3, vcc, 0, v1, vcc
	s_cmp_lg_u32 s32, 0
	s_cbranch_scc1 .Lidx_skipq1
	global_load_dwordx4 v[128:131], v[0:1], off
	global_load_dwordx4 v[132:135], v[0:1], off offset:32
	global_load_dwordx4 v[136:139], v[2:3], off
	global_load_dwordx4 v[140:143], v[2:3], off offset:32
	global_load_dwordx4 v[144:147], v[0:1], off offset:64
	global_load_dwordx4 v[148:151], v[0:1], off offset:96
	global_load_dwordx4 v[152:155], v[2:3], off offset:64
	global_load_dwordx4 v[156:159], v[2:3], off offset:96
	global_load_dwordx4 v[160:163], v[0:1], off offset:128
	global_load_dwordx4 v[164:167], v[0:1], off offset:160
	global_load_dwordx4 v[168:171], v[2:3], off offset:128
	global_load_dwordx4 v[172:175], v[2:3], off offset:160
	global_load_dwordx4 v[176:179], v[0:1], off offset:192
	global_load_dwordx4 v[180:183], v[0:1], off offset:224
	global_load_dwordx4 v[184:187], v[2:3], off offset:192
	global_load_dwordx4 v[188:191], v[2:3], off offset:224
.Lidx_skipq1:
	s_add_u32 s4, s80, s4
	v_lshlrev_b32_e32 v0, 2, v4
	s_addc_u32 s5, s81, s5
	v_ashrrev_i32_e32 v1, 31, v0
	v_lshl_add_u64 v[0:1], v[0:1], 2, s[4:5]
	s_waitcnt lgkmcnt(0)
	s_cmp_lg_u32 s32, 0
	s_cbranch_scc1 .Lidx_skipq2
	global_load_dwordx4 v[124:127], v[0:1], off
	global_load_dwordx4 v[116:119], v[0:1], off offset:32
	global_load_dwordx4 v[120:123], v[0:1], off offset:128
	global_load_dwordx4 v[112:115], v[0:1], off offset:160
	global_load_dwordx4 v[108:111], v[0:1], off offset:64
	global_load_dwordx4 v[100:103], v[0:1], off offset:96
	global_load_dwordx4 v[104:107], v[0:1], off offset:192
	global_load_dwordx4 v[96:99], v[0:1], off offset:224
.Lidx_skipq2:
	s_mov_b32 s32, 0
	s_add_u32 s4, s33, s0
	s_addc_u32 s5, s34, s1
	s_mov_b32 m0, s39
	v_lshl_add_u64 v[0:1], v[212:213], 1, s[4:5]
	s_barrier
	global_load_lds_dwordx4 v[0:1], off
	v_lshl_add_u64 v[0:1], v[210:211], 1, s[4:5]
	s_mov_b32 m0, s44
	s_cmp_lt_u32 s6, 4
	global_load_lds_dwordx4 v[0:1], off
	s_cbranch_scc1 .LBB0_1160
	s_add_u32 s8, s4, 0x4000
	s_addc_u32 s9, s5, 0
	s_mov_b32 m0, s45
	v_lshl_add_u64 v[0:1], v[212:213], 1, s[8:9]
	global_load_lds_dwordx4 v[0:1], off
	v_lshl_add_u64 v[0:1], v[210:211], 1, s[8:9]
	s_mov_b32 m0, s46
	s_nop 0
	global_load_lds_dwordx4 v[0:1], off
